# K-loops: load segments run at s_setprio 2 (above the MFMA bursts' priority 1) instead of 0
# baseline (speedup 1.0000x reference)
; #define PG8_STAGE(bufoff, gbase, voff) do { _Pragma("unroll") for (int _i = 0; _i < 2; ++_i) \
;         __builtin_amdgcn_global_load_lds((const unsigned*)((const char*)(gbase) + (voff)[_i]), (LAS unsigned*)(lds + (bufoff) + ldsw + _i * 8192), 16, 0, 0); } while (0)
; #define PG8_LDA(dst, b, h) do { _Pragma("unroll") for (int m = 0; m < 4; ++m) _Pragma("unroll") for (int k = 0; k < 2; ++k) dst[m][k] = *(const LAS bf16x8*)(lds + PG8_SA(b, h) + aoff + m * 2048 + k * 1024); } while (0)
; #define PG8_LDB(dst, b, h) do { _Pragma("unroll") for (int n = 0; n < 2; ++n) _Pragma("unroll") for (int k = 0; k < 2; ++k) dst[n][k] = *(const LAS bf16x8*)(lds + PG8_SB(b, h) + boff + n * 2048 + k * 1024); } while (0)
; #define PG8_MMA(ai, bj, At, Bt) do { __builtin_amdgcn_s_setprio(1); _Pragma("unroll") for (int m = 0; m < 4; ++m) _Pragma("unroll") for (int n = 0; n < 2; ++n) _Pragma("unroll") for (int k = 0; k < 2; ++k) \
;         acc[ai][bj][m][n] = __builtin_amdgcn_mfma_f32_16x16x32_bf16(Bt[n][k], At[m][k], acc[ai][bj][m][n], 0, 0, 0); __builtin_amdgcn_s_setprio(0); } while (0)
; #define PG8_WAIT_V(n) asm volatile("s_waitcnt vmcnt(" #n ")" ::: "memory")
; #define PG8_WAIT_L(n) asm volatile("s_waitcnt lgkmcnt(" #n ")" ::: "memory")
; #define PG8_BAR __builtin_amdgcn_s_barrier()
; #define PG8_SCHED __builtin_amdgcn_sched_barrier(0)
;     ...
;         for (int t = 0; t < nt; t += 2) {
;             const bool last = (t == nt - 2);
;             const char* a1 = cA + (size_t)(t + 1) * kstep;
;             const char* a2 = last ? nA : cA + (size_t)(t + 2) * kstep; const char* b2 = last ? nB : cB + (size_t)(t + 2) * kstep;
;             const char* a3 = a2 + kstep; const char* b3 = b2 + kstep;
;             PG8_LDB(B0, 0, 0); PG8_LDB(B1, 0, 1); PG8_SCHED; PG8_LDA(At, 0, 0); PG8_STAGE(PG8_SA(1, 1), a1 + hstepA, voffA);
;             PG8_WAIT_V(8); PG8_WAIT_L(0); PG8_BAR; PG8_MMA(0, 0, At, B0); PG8_MMA(0, 1, At, B1); PG8_BAR; PG8_SCHED;
;             PG8_LDA(At, 0, 1); PG8_STAGE(PG8_SB(0, 0), b2, voffB); PG8_STAGE(PG8_SB(0, 1), b2 + hstepB, voffB); PG8_STAGE(PG8_SA(0, 0), a2, voffA);
;             PG8_WAIT_V(8); PG8_WAIT_L(0); PG8_BAR; PG8_MMA(1, 0, At, B0); PG8_MMA(1, 1, At, B1); PG8_BAR; PG8_SCHED;
.LBB0_159:
	s_add_i32 s38, s8, 2
	s_add_u32 s26, s12, s0
	s_addc_u32 s9, s13, s1
	s_add_i32 s27, 0, 0x10000
	s_cmp_eq_u32 s63, s8
	s_cselect_b32 s9, s18, s9
	s_cselect_b32 s8, s19, s26
	s_cselect_b64 vcc, -1, 0
	s_add_i32 s26, 0, 0x14000
	v_lshl_add_u64 v[150:151], v[188:189], 0, s[0:1]
	v_add_u32_e32 v146, s27, v226
	v_add_u32_e32 v162, s26, v226
	ds_read_b128 v[134:137], v146
	ds_read_b128 v[138:141], v146 offset:1024
	ds_read_b128 v[142:145], v146 offset:2048
	ds_read_b128 v[146:149], v146 offset:3072
	v_cndmask_b32_e32 v205, v151, v132, vcc
	v_cndmask_b32_e32 v204, v150, v133, vcc
	ds_read_b128 v[150:153], v162
	ds_read_b128 v[154:157], v162 offset:1024
	ds_read_b128 v[158:161], v162 offset:2048
	ds_read_b128 v[162:165], v162 offset:3072
	v_lshl_add_u64 v[212:213], s[12:13], 0, v[130:131]
	s_add_i32 m0, s20, 0xc000
	ds_read_b128 v[166:169], v227
	ds_read_b128 v[170:173], v227 offset:1024
	ds_read_b128 v[174:177], v227 offset:2048
	ds_read_b128 v[178:181], v227 offset:3072
	ds_read_b128 v[230:233], v227 offset:4096
	ds_read_b128 v[234:237], v227 offset:5120
	ds_read_b128 v[238:241], v227 offset:6144
	ds_read_b128 v[242:245], v227 offset:7168
	global_load_lds_dwordx4 v[212:213], off
	v_lshl_add_u64 v[212:213], s[12:13], 0, v[128:129]
	s_add_i32 m0, s20, 0xe000
	s_nop 0
	global_load_lds_dwordx4 v[212:213], off
	s_waitcnt vmcnt(8)
	s_waitcnt lgkmcnt(0)
	s_barrier
	s_setprio 1
	s_waitcnt lgkmcnt(0)
	v_mfma_f32_16x16x32_bf16 v[124:127], v[134:137], v[166:169], v[124:127]
	v_mfma_f32_16x16x32_bf16 v[0:3], v[142:145], v[166:169], v[0:3]
	v_mfma_f32_16x16x32_bf16 v[120:123], v[134:137], v[174:177], v[120:123]
	v_mfma_f32_16x16x32_bf16 v[116:119], v[142:145], v[174:177], v[116:119]
	v_mfma_f32_16x16x32_bf16 v[112:115], v[134:137], v[230:233], v[112:115]
	v_mfma_f32_16x16x32_bf16 v[108:111], v[142:145], v[230:233], v[108:111]
	v_mfma_f32_16x16x32_bf16 v[104:107], v[134:137], v[238:241], v[104:107]
	v_mfma_f32_16x16x32_bf16 v[4:7], v[142:145], v[238:241], v[4:7]
	v_mfma_f32_16x16x32_bf16 v[124:127], v[138:141], v[170:173], v[124:127]
	v_mfma_f32_16x16x32_bf16 v[0:3], v[146:149], v[170:173], v[0:3]
	v_mfma_f32_16x16x32_bf16 v[120:123], v[138:141], v[178:181], v[120:123]
	v_mfma_f32_16x16x32_bf16 v[116:119], v[146:149], v[178:181], v[116:119]
	v_mfma_f32_16x16x32_bf16 v[112:115], v[138:141], v[234:237], v[112:115]
	v_mfma_f32_16x16x32_bf16 v[108:111], v[146:149], v[234:237], v[108:111]
	v_mfma_f32_16x16x32_bf16 v[104:107], v[138:141], v[242:245], v[104:107]
	v_mfma_f32_16x16x32_bf16 v[4:7], v[146:149], v[242:245], v[4:7]
	s_setprio 0
	s_setprio 1
	v_mfma_f32_16x16x32_bf16 v[100:103], v[150:153], v[166:169], v[100:103]
	v_mfma_f32_16x16x32_bf16 v[96:99], v[158:161], v[166:169], v[96:99]
	v_mfma_f32_16x16x32_bf16 v[92:95], v[150:153], v[174:177], v[92:95]
	v_mfma_f32_16x16x32_bf16 v[88:91], v[158:161], v[174:177], v[88:91]
	v_mfma_f32_16x16x32_bf16 v[84:87], v[150:153], v[230:233], v[84:87]
	v_mfma_f32_16x16x32_bf16 v[80:83], v[158:161], v[230:233], v[80:83]
	v_mfma_f32_16x16x32_bf16 v[76:79], v[150:153], v[238:241], v[76:79]
	v_mfma_f32_16x16x32_bf16 v[72:75], v[158:161], v[238:241], v[72:75]
	v_mfma_f32_16x16x32_bf16 v[100:103], v[154:157], v[170:173], v[100:103]
	v_mfma_f32_16x16x32_bf16 v[96:99], v[162:165], v[170:173], v[96:99]
	v_mfma_f32_16x16x32_bf16 v[92:95], v[154:157], v[178:181], v[92:95]
	v_mfma_f32_16x16x32_bf16 v[88:91], v[162:165], v[178:181], v[88:91]
	v_mfma_f32_16x16x32_bf16 v[84:87], v[154:157], v[234:237], v[84:87]
	v_mfma_f32_16x16x32_bf16 v[80:83], v[162:165], v[234:237], v[80:83]
	v_mfma_f32_16x16x32_bf16 v[76:79], v[154:157], v[242:245], v[76:79]
	v_mfma_f32_16x16x32_bf16 v[72:75], v[162:165], v[242:245], v[72:75]
	s_setprio 2
	s_barrier
	s_add_i32 s27, s27, s11
	v_lshl_add_u64 v[212:213], v[204:205], 0, v[192:193]
	s_mov_b32 m0, s27
	ds_read_b128 v[166:169], v227 offset:16384
	ds_read_b128 v[170:173], v227 offset:17408
	ds_read_b128 v[174:177], v227 offset:18432
	ds_read_b128 v[178:181], v227 offset:19456
	ds_read_b128 v[230:233], v227 offset:20480
	ds_read_b128 v[234:237], v227 offset:21504
	ds_read_b128 v[238:241], v227 offset:22528
	ds_read_b128 v[242:245], v227 offset:23552
	global_load_lds_dwordx4 v[212:213], off
	v_lshl_add_u64 v[218:219], v[204:205], 0, v[196:197]
	s_add_i32 m0, s27, 0x2000
	v_lshl_add_u64 v[204:205], v[204:205], 0, v[198:199]
	s_add_i32 s26, s26, s11
	global_load_lds_dwordx4 v[218:219], off
	v_lshl_add_u64 v[246:247], v[204:205], 0, v[192:193]
	s_mov_b32 m0, s26
	v_lshl_add_u64 v[204:205], v[204:205], 0, v[196:197]
	global_load_lds_dwordx4 v[246:247], off
	s_add_i32 m0, s26, 0x2000
	v_lshl_add_u64 v[248:249], s[8:9], 0, v[190:191]
	global_load_lds_dwordx4 v[204:205], off
	s_mov_b32 m0, s20
	v_lshl_add_u64 v[250:251], s[8:9], 0, v[194:195]
	global_load_lds_dwordx4 v[248:249], off
	s_mov_b32 m0, s48
	s_nop 0
	global_load_lds_dwordx4 v[250:251], off
	s_waitcnt vmcnt(8)
	s_waitcnt lgkmcnt(0)
	s_barrier
; #define PG8_STAGE(bufoff, gbase, voff) do { _Pragma("unroll") for (int _i = 0; _i < 2; ++_i) \
;         __builtin_amdgcn_global_load_lds((const unsigned*)((const char*)(gbase) + (voff)[_i]), (LAS unsigned*)(lds + (bufoff) + ldsw + _i * 8192), 16, 0, 0); } while (0)
; #define PG8_LDA(dst, b, h) do { _Pragma("unroll") for (int m = 0; m < 4; ++m) _Pragma("unroll") for (int k = 0; k < 2; ++k) dst[m][k] = *(const LAS bf16x8*)(lds + PG8_SA(b, h) + aoff + m * 2048 + k * 1024); } while (0)
; #define PG8_LDB(dst, b, h) do { _Pragma("unroll") for (int n = 0; n < 2; ++n) _Pragma("unroll") for (int k = 0; k < 2; ++k) dst[n][k] = *(const LAS bf16x8*)(lds + PG8_SB(b, h) + boff + n * 2048 + k * 1024); } while (0)
; #define PG8_MMA(ai, bj, At, Bt) do { __builtin_amdgcn_s_setprio(1); _Pragma("unroll") for (int m = 0; m < 4; ++m) _Pragma("unroll") for (int n = 0; n < 2; ++n) _Pragma("unroll") for (int k = 0; k < 2; ++k) \
;         acc[ai][bj][m][n] = __builtin_amdgcn_mfma_f32_16x16x32_bf16(Bt[n][k], At[m][k], acc[ai][bj][m][n], 0, 0, 0); __builtin_amdgcn_s_setprio(0); } while (0)
; #define PG8_WAIT_V(n) asm volatile("s_waitcnt vmcnt(" #n ")" ::: "memory")
; #define PG8_WAIT_L(n) asm volatile("s_waitcnt lgkmcnt(" #n ")" ::: "memory")
; #define PG8_BAR __builtin_amdgcn_s_barrier()
; #define PG8_SCHED __builtin_amdgcn_sched_barrier(0)
;     ...
;             PG8_WAIT_V(8); PG8_WAIT_L(0); PG8_BAR; PG8_MMA(1, 0, At, B0); PG8_MMA(1, 1, At, B1); PG8_BAR; PG8_SCHED;
;             PG8_LDB(B0, 1, 0); PG8_LDB(B1, 1, 1); PG8_SCHED; PG8_LDA(At, 1, 0); PG8_STAGE(PG8_SA(0, 1), a2 + hstepA, voffA);
;             PG8_WAIT_V(8); PG8_WAIT_L(0); PG8_BAR; PG8_MMA(0, 0, At, B0); PG8_MMA(0, 1, At, B1); PG8_BAR; PG8_SCHED;
	s_setprio 1
	s_waitcnt lgkmcnt(0)
	v_mfma_f32_16x16x32_bf16 v[68:71], v[134:137], v[166:169], v[68:71]
	v_mfma_f32_16x16x32_bf16 v[8:11], v[142:145], v[166:169], v[8:11]
	v_mfma_f32_16x16x32_bf16 v[64:67], v[134:137], v[174:177], v[64:67]
	v_mfma_f32_16x16x32_bf16 v[60:63], v[142:145], v[174:177], v[60:63]
	v_mfma_f32_16x16x32_bf16 v[56:59], v[134:137], v[230:233], v[56:59]
	v_mfma_f32_16x16x32_bf16 v[52:55], v[142:145], v[230:233], v[52:55]
	v_mfma_f32_16x16x32_bf16 v[48:51], v[134:137], v[238:241], v[48:51]
	v_mfma_f32_16x16x32_bf16 v[12:15], v[142:145], v[238:241], v[12:15]
	v_mfma_f32_16x16x32_bf16 v[68:71], v[138:141], v[170:173], v[68:71]
	v_mfma_f32_16x16x32_bf16 v[8:11], v[146:149], v[170:173], v[8:11]
	v_mfma_f32_16x16x32_bf16 v[64:67], v[138:141], v[178:181], v[64:67]
	v_mfma_f32_16x16x32_bf16 v[60:63], v[146:149], v[178:181], v[60:63]
	v_mfma_f32_16x16x32_bf16 v[56:59], v[138:141], v[234:237], v[56:59]
	v_mfma_f32_16x16x32_bf16 v[52:55], v[146:149], v[234:237], v[52:55]
	v_mfma_f32_16x16x32_bf16 v[48:51], v[138:141], v[242:245], v[48:51]
	v_mfma_f32_16x16x32_bf16 v[12:15], v[146:149], v[242:245], v[12:15]
	s_setprio 0
	s_setprio 1
	v_mfma_f32_16x16x32_bf16 v[44:47], v[150:153], v[166:169], v[44:47]
	v_mfma_f32_16x16x32_bf16 v[40:43], v[158:161], v[166:169], v[40:43]
	v_mfma_f32_16x16x32_bf16 v[36:39], v[150:153], v[174:177], v[36:39]
	v_mfma_f32_16x16x32_bf16 v[32:35], v[158:161], v[174:177], v[32:35]
	v_mfma_f32_16x16x32_bf16 v[28:31], v[150:153], v[230:233], v[28:31]
	v_mfma_f32_16x16x32_bf16 v[24:27], v[158:161], v[230:233], v[24:27]
	v_mfma_f32_16x16x32_bf16 v[20:23], v[150:153], v[238:241], v[20:23]
	v_mfma_f32_16x16x32_bf16 v[16:19], v[158:161], v[238:241], v[16:19]
	v_mfma_f32_16x16x32_bf16 v[44:47], v[154:157], v[170:173], v[44:47]
	v_mfma_f32_16x16x32_bf16 v[40:43], v[162:165], v[170:173], v[40:43]
	v_mfma_f32_16x16x32_bf16 v[36:39], v[154:157], v[178:181], v[36:39]
	v_mfma_f32_16x16x32_bf16 v[32:35], v[162:165], v[178:181], v[32:35]
	v_mfma_f32_16x16x32_bf16 v[28:31], v[154:157], v[234:237], v[28:31]
	v_mfma_f32_16x16x32_bf16 v[24:27], v[162:165], v[234:237], v[24:27]
	v_mfma_f32_16x16x32_bf16 v[20:23], v[154:157], v[242:245], v[20:23]
	v_mfma_f32_16x16x32_bf16 v[16:19], v[162:165], v[242:245], v[16:19]
	s_setprio 2
	s_barrier
	s_add_i32 s26, 0, 0x18000
	s_add_i32 s27, 0, 0x1c000
	v_add_u32_e32 v146, s26, v226
	v_add_u32_e32 v162, s27, v226
	ds_read_b128 v[134:137], v146
	ds_read_b128 v[138:141], v146 offset:1024
	ds_read_b128 v[142:145], v146 offset:2048
	ds_read_b128 v[146:149], v146 offset:3072
	ds_read_b128 v[150:153], v162
	ds_read_b128 v[154:157], v162 offset:1024
	ds_read_b128 v[158:161], v162 offset:2048
	ds_read_b128 v[162:165], v162 offset:3072
	s_add_u32 s8, s8, s10
	s_addc_u32 s9, s9, 0
	s_mov_b32 m0, s51
	v_lshl_add_u64 v[214:215], s[8:9], 0, v[190:191]
	ds_read_b128 v[166:169], v227 offset:32768
	ds_read_b128 v[170:173], v227 offset:33792
	ds_read_b128 v[174:177], v227 offset:34816
	ds_read_b128 v[178:181], v227 offset:35840
	ds_read_b128 v[230:233], v227 offset:36864
	ds_read_b128 v[234:237], v227 offset:37888
	ds_read_b128 v[238:241], v227 offset:38912
	ds_read_b128 v[242:245], v227 offset:39936
	global_load_lds_dwordx4 v[214:215], off
	v_lshl_add_u64 v[214:215], s[8:9], 0, v[194:195]
	s_mov_b32 m0, s62
	s_nop 0
	global_load_lds_dwordx4 v[214:215], off
	s_waitcnt vmcnt(8)
	s_waitcnt lgkmcnt(0)
	s_barrier
	s_setprio 1
	s_waitcnt lgkmcnt(0)
	v_mfma_f32_16x16x32_bf16 v[124:127], v[134:137], v[166:169], v[124:127]
	v_mfma_f32_16x16x32_bf16 v[0:3], v[142:145], v[166:169], v[0:3]
	v_mfma_f32_16x16x32_bf16 v[120:123], v[134:137], v[174:177], v[120:123]
	v_mfma_f32_16x16x32_bf16 v[116:119], v[142:145], v[174:177], v[116:119]
	v_mfma_f32_16x16x32_bf16 v[112:115], v[134:137], v[230:233], v[112:115]
	v_mfma_f32_16x16x32_bf16 v[108:111], v[142:145], v[230:233], v[108:111]
	v_mfma_f32_16x16x32_bf16 v[104:107], v[134:137], v[238:241], v[104:107]
	v_mfma_f32_16x16x32_bf16 v[4:7], v[142:145], v[238:241], v[4:7]
	v_mfma_f32_16x16x32_bf16 v[124:127], v[138:141], v[170:173], v[124:127]
	v_mfma_f32_16x16x32_bf16 v[0:3], v[146:149], v[170:173], v[0:3]
	v_mfma_f32_16x16x32_bf16 v[120:123], v[138:141], v[178:181], v[120:123]
	v_mfma_f32_16x16x32_bf16 v[116:119], v[146:149], v[178:181], v[116:119]
	v_mfma_f32_16x16x32_bf16 v[112:115], v[138:141], v[234:237], v[112:115]
	v_mfma_f32_16x16x32_bf16 v[108:111], v[146:149], v[234:237], v[108:111]
	v_mfma_f32_16x16x32_bf16 v[104:107], v[138:141], v[242:245], v[104:107]
	v_mfma_f32_16x16x32_bf16 v[4:7], v[146:149], v[242:245], v[4:7]
	s_setprio 0
	s_setprio 1
	v_mfma_f32_16x16x32_bf16 v[100:103], v[150:153], v[166:169], v[100:103]
	v_mfma_f32_16x16x32_bf16 v[96:99], v[158:161], v[166:169], v[96:99]
	v_mfma_f32_16x16x32_bf16 v[92:95], v[150:153], v[174:177], v[92:95]
	v_mfma_f32_16x16x32_bf16 v[88:91], v[158:161], v[174:177], v[88:91]
	v_mfma_f32_16x16x32_bf16 v[84:87], v[150:153], v[230:233], v[84:87]
	v_mfma_f32_16x16x32_bf16 v[80:83], v[158:161], v[230:233], v[80:83]
	v_mfma_f32_16x16x32_bf16 v[76:79], v[150:153], v[238:241], v[76:79]
	v_mfma_f32_16x16x32_bf16 v[72:75], v[158:161], v[238:241], v[72:75]
	v_mfma_f32_16x16x32_bf16 v[100:103], v[154:157], v[170:173], v[100:103]
	v_mfma_f32_16x16x32_bf16 v[96:99], v[162:165], v[170:173], v[96:99]
	v_mfma_f32_16x16x32_bf16 v[92:95], v[154:157], v[178:181], v[92:95]
	v_mfma_f32_16x16x32_bf16 v[88:91], v[162:165], v[178:181], v[88:91]
	v_mfma_f32_16x16x32_bf16 v[84:87], v[154:157], v[234:237], v[84:87]
	v_mfma_f32_16x16x32_bf16 v[80:83], v[162:165], v[234:237], v[80:83]
	v_mfma_f32_16x16x32_bf16 v[76:79], v[154:157], v[242:245], v[76:79]
	v_mfma_f32_16x16x32_bf16 v[72:75], v[162:165], v[242:245], v[72:75]
	s_setprio 2
	s_barrier
; #define PG8_STAGE(bufoff, gbase, voff) do { _Pragma("unroll") for (int _i = 0; _i < 2; ++_i) \
;         __builtin_amdgcn_global_load_lds((const unsigned*)((const char*)(gbase) + (voff)[_i]), (LAS unsigned*)(lds + (bufoff) + ldsw + _i * 8192), 16, 0, 0); } while (0)
; #define PG8_LDA(dst, b, h) do { _Pragma("unroll") for (int m = 0; m < 4; ++m) _Pragma("unroll") for (int k = 0; k < 2; ++k) dst[m][k] = *(const LAS bf16x8*)(lds + PG8_SA(b, h) + aoff + m * 2048 + k * 1024); } while (0)
; #define PG8_MMA(ai, bj, At, Bt) do { __builtin_amdgcn_s_setprio(1); _Pragma("unroll") for (int m = 0; m < 4; ++m) _Pragma("unroll") for (int n = 0; n < 2; ++n) _Pragma("unroll") for (int k = 0; k < 2; ++k) \
;         acc[ai][bj][m][n] = __builtin_amdgcn_mfma_f32_16x16x32_bf16(Bt[n][k], At[m][k], acc[ai][bj][m][n], 0, 0, 0); __builtin_amdgcn_s_setprio(0); } while (0)
; #define PG8_WAIT_V(n) asm volatile("s_waitcnt vmcnt(" #n ")" ::: "memory")
; #define PG8_WAIT_L(n) asm volatile("s_waitcnt lgkmcnt(" #n ")" ::: "memory")
; #define PG8_BAR __builtin_amdgcn_s_barrier()
; #define PG8_SCHED __builtin_amdgcn_sched_barrier(0)
;     ...
;             PG8_LDA(At, 1, 1); PG8_STAGE(PG8_SB(1, 0), b3, voffB); PG8_STAGE(PG8_SB(1, 1), b3 + hstepB, voffB); PG8_STAGE(PG8_SA(1, 0), a3, voffA);
;             PG8_WAIT_V(8); PG8_WAIT_L(0); PG8_BAR; PG8_MMA(1, 0, At, B0); PG8_MMA(1, 1, At, B1); PG8_BAR; PG8_SCHED;
;         }
;         if (wr == 0) PG8_BAR;
	s_add_i32 s8, s26, s11
	v_lshl_add_u64 v[212:213], v[212:213], 0, s[70:71]
	s_mov_b32 m0, s8
	ds_read_b128 v[166:169], v227 offset:49152
	ds_read_b128 v[170:173], v227 offset:50176
	ds_read_b128 v[174:177], v227 offset:51200
	ds_read_b128 v[178:181], v227 offset:52224
	ds_read_b128 v[230:233], v227 offset:53248
	ds_read_b128 v[234:237], v227 offset:54272
	ds_read_b128 v[238:241], v227 offset:55296
	ds_read_b128 v[242:245], v227 offset:56320
	global_load_lds_dwordx4 v[212:213], off
	v_lshl_add_u64 v[212:213], v[218:219], 0, s[70:71]
	s_add_i32 m0, s8, 0x2000
	s_add_i32 s8, s27, s11
	global_load_lds_dwordx4 v[212:213], off
	v_lshl_add_u64 v[212:213], v[246:247], 0, s[70:71]
	s_mov_b32 m0, s8
	v_lshl_add_u64 v[204:205], v[204:205], 0, s[70:71]
	global_load_lds_dwordx4 v[212:213], off
	s_add_i32 m0, s8, 0x2000
	s_nop 0
	global_load_lds_dwordx4 v[204:205], off
	v_lshl_add_u64 v[204:205], v[248:249], 0, s[70:71]
	s_mov_b32 m0, s65
	s_nop 0
	global_load_lds_dwordx4 v[204:205], off
	v_lshl_add_u64 v[204:205], v[250:251], 0, s[70:71]
	s_mov_b32 m0, s49
	s_nop 0
	global_load_lds_dwordx4 v[204:205], off
	s_waitcnt vmcnt(8)
	s_waitcnt lgkmcnt(0)
	s_barrier
	s_setprio 1
	s_waitcnt lgkmcnt(0)
	v_mfma_f32_16x16x32_bf16 v[68:71], v[134:137], v[166:169], v[68:71]
	v_mfma_f32_16x16x32_bf16 v[8:11], v[142:145], v[166:169], v[8:11]
	v_mfma_f32_16x16x32_bf16 v[64:67], v[134:137], v[174:177], v[64:67]
	v_mfma_f32_16x16x32_bf16 v[60:63], v[142:145], v[174:177], v[60:63]
	v_mfma_f32_16x16x32_bf16 v[56:59], v[134:137], v[230:233], v[56:59]
	v_mfma_f32_16x16x32_bf16 v[52:55], v[142:145], v[230:233], v[52:55]
	v_mfma_f32_16x16x32_bf16 v[48:51], v[134:137], v[238:241], v[48:51]
	v_mfma_f32_16x16x32_bf16 v[12:15], v[142:145], v[238:241], v[12:15]
	v_mfma_f32_16x16x32_bf16 v[68:71], v[138:141], v[170:173], v[68:71]
	v_mfma_f32_16x16x32_bf16 v[8:11], v[146:149], v[170:173], v[8:11]
	v_mfma_f32_16x16x32_bf16 v[64:67], v[138:141], v[178:181], v[64:67]
	v_mfma_f32_16x16x32_bf16 v[60:63], v[146:149], v[178:181], v[60:63]
	v_mfma_f32_16x16x32_bf16 v[56:59], v[138:141], v[234:237], v[56:59]
	v_mfma_f32_16x16x32_bf16 v[52:55], v[146:149], v[234:237], v[52:55]
	v_mfma_f32_16x16x32_bf16 v[48:51], v[138:141], v[242:245], v[48:51]
	v_mfma_f32_16x16x32_bf16 v[12:15], v[146:149], v[242:245], v[12:15]
	s_setprio 0
	s_setprio 1
	v_mfma_f32_16x16x32_bf16 v[44:47], v[150:153], v[166:169], v[44:47]
	v_mfma_f32_16x16x32_bf16 v[40:43], v[158:161], v[166:169], v[40:43]
	v_mfma_f32_16x16x32_bf16 v[36:39], v[150:153], v[174:177], v[36:39]
	v_mfma_f32_16x16x32_bf16 v[32:35], v[158:161], v[174:177], v[32:35]
	v_mfma_f32_16x16x32_bf16 v[28:31], v[150:153], v[230:233], v[28:31]
	v_mfma_f32_16x16x32_bf16 v[24:27], v[158:161], v[230:233], v[24:27]
	v_mfma_f32_16x16x32_bf16 v[20:23], v[150:153], v[238:241], v[20:23]
	v_mfma_f32_16x16x32_bf16 v[16:19], v[158:161], v[238:241], v[16:19]
	v_mfma_f32_16x16x32_bf16 v[44:47], v[154:157], v[170:173], v[44:47]
	v_mfma_f32_16x16x32_bf16 v[40:43], v[162:165], v[170:173], v[40:43]
	v_mfma_f32_16x16x32_bf16 v[36:39], v[154:157], v[178:181], v[36:39]
	v_mfma_f32_16x16x32_bf16 v[32:35], v[162:165], v[178:181], v[32:35]
	v_mfma_f32_16x16x32_bf16 v[28:31], v[154:157], v[234:237], v[28:31]
	v_mfma_f32_16x16x32_bf16 v[24:27], v[162:165], v[234:237], v[24:27]
	v_mfma_f32_16x16x32_bf16 v[20:23], v[154:157], v[242:245], v[20:23]
	v_mfma_f32_16x16x32_bf16 v[16:19], v[162:165], v[242:245], v[16:19]
	s_setprio 2
	s_barrier
	s_add_u32 s0, s0, 0x100
	s_addc_u32 s1, s1, 0
	v_lshl_add_u64 v[130:131], v[130:131], 0, s[94:95]
	v_lshl_add_u64 v[128:129], v[128:129], 0, s[94:95]
	s_cmp_ge_u32 s38, s52
	s_mov_b32 s8, s38
	s_cbranch_scc0 .LBB0_159
	v_readlane_b32 s0, v254, 50
	v_readlane_b32 s1, v254, 51
	s_and_b64 vcc, exec, s[0:1]
	s_movk_i32 s67, 0xfe
	s_cbranch_vccz .LBB0_162
	s_barrier

; #define PG8_STAGE(bufoff, gbase, voff) do { _Pragma("unroll") for (int _i = 0; _i < 2; ++_i) \
;         __builtin_amdgcn_global_load_lds((const unsigned*)((const char*)(gbase) + (voff)[_i]), (LAS unsigned*)(lds + (bufoff) + ldsw + _i * 8192), 16, 0, 0); } while (0)
; #define PG8_LDA(dst, b, h) do { _Pragma("unroll") for (int m = 0; m < 4; ++m) _Pragma("unroll") for (int k = 0; k < 2; ++k) dst[m][k] = *(const LAS bf16x8*)(lds + PG8_SA(b, h) + aoff + m * 2048 + k * 1024); } while (0)
; #define PG8_LDB(dst, b, h) do { _Pragma("unroll") for (int n = 0; n < 2; ++n) _Pragma("unroll") for (int k = 0; k < 2; ++k) dst[n][k] = *(const LAS bf16x8*)(lds + PG8_SB(b, h) + boff + n * 2048 + k * 1024); } while (0)
; #define PG8_MMA(ai, bj, At, Bt) do { __builtin_amdgcn_s_setprio(1); _Pragma("unroll") for (int m = 0; m < 4; ++m) _Pragma("unroll") for (int n = 0; n < 2; ++n) _Pragma("unroll") for (int k = 0; k < 2; ++k) \
;         acc[ai][bj][m][n] = __builtin_amdgcn_mfma_f32_16x16x32_bf16(Bt[n][k], At[m][k], acc[ai][bj][m][n], 0, 0, 0); __builtin_amdgcn_s_setprio(0); } while (0)
; #define PG8_WAIT_V(n) asm volatile("s_waitcnt vmcnt(" #n ")" ::: "memory")
; #define PG8_WAIT_L(n) asm volatile("s_waitcnt lgkmcnt(" #n ")" ::: "memory")
; #define PG8_BAR __builtin_amdgcn_s_barrier()
; #define PG8_SCHED __builtin_amdgcn_sched_barrier(0)
;     ...
;         for (int t = 0; t < nt; t += 2) {
;             const bool last = (t == nt - 2);
;             const char* a1 = cA + (size_t)(t + 1) * kstep;
;             const char* a2 = last ? nA : cA + (size_t)(t + 2) * kstep; const char* b2 = last ? nB : cB + (size_t)(t + 2) * kstep;
;             const char* a3 = a2 + kstep; const char* b3 = b2 + kstep;
;             PG8_LDB(B0, 0, 0); PG8_LDB(B1, 0, 1); PG8_SCHED; PG8_LDA(At, 0, 0); PG8_STAGE(PG8_SA(1, 1), a1 + hstepA, voffA);
;             PG8_WAIT_V(8); PG8_WAIT_L(0); PG8_BAR; PG8_MMA(0, 0, At, B0); PG8_MMA(0, 1, At, B1); PG8_BAR; PG8_SCHED;
;             PG8_LDA(At, 0, 1); PG8_STAGE(PG8_SB(0, 0), b2, voffB); PG8_STAGE(PG8_SB(0, 1), b2 + hstepB, voffB); PG8_STAGE(PG8_SA(0, 0), a2, voffA);
;             PG8_WAIT_V(8); PG8_WAIT_L(0); PG8_BAR; PG8_MMA(1, 0, At, B0); PG8_MMA(1, 1, At, B1); PG8_BAR; PG8_SCHED;
.LBB0_318:
	s_add_i32 s57, s38, 2
	s_add_u32 s19, s2, s0
	s_addc_u32 s27, s3, s1
	s_add_i32 s58, 0, 0x10000
	s_cmp_eq_u32 s51, s38
	s_cselect_b32 s39, s13, s27
	s_cselect_b32 s38, s56, s19
	s_cselect_b64 vcc, -1, 0
	s_add_i32 s19, 0, 0x14000
	v_lshl_add_u64 v[150:151], v[160:161], 0, s[0:1]
	v_add_u32_e32 v146, s58, v181
	s_waitcnt lgkmcnt(0)
	v_add_u32_e32 v178, s19, v181
	ds_read_b128 v[134:137], v146
	ds_read_b128 v[138:141], v146 offset:1024
	ds_read_b128 v[142:145], v146 offset:2048
	ds_read_b128 v[146:149], v146 offset:3072
	v_cndmask_b32_e32 v159, v151, v132, vcc
	v_cndmask_b32_e32 v158, v150, v133, vcc
	ds_read_b128 v[150:153], v178
	ds_read_b128 v[154:157], v178 offset:1024
	ds_read_b128 v[174:177], v178 offset:2048
	ds_read_b128 v[190:193], v178 offset:3072
	v_lshl_add_u64 v[178:179], s[2:3], 0, v[130:131]
	s_add_i32 m0, s11, 0xc000
	ds_read_b128 v[194:197], v188
	ds_read_b128 v[198:201], v188 offset:1024
	ds_read_b128 v[202:205], v188 offset:2048
	ds_read_b128 v[224:227], v188 offset:3072
	ds_read_b128 v[228:231], v188 offset:4096
	ds_read_b128 v[232:235], v188 offset:5120
	ds_read_b128 v[236:239], v188 offset:6144
	ds_read_b128 v[240:243], v188 offset:7168
	global_load_lds_dwordx4 v[178:179], off
	v_lshl_add_u64 v[178:179], s[2:3], 0, v[128:129]
	s_add_i32 m0, s11, 0xe000
	s_nop 0
	global_load_lds_dwordx4 v[178:179], off
	s_waitcnt vmcnt(8)
	s_waitcnt lgkmcnt(0)
	s_barrier
	s_setprio 1
	s_waitcnt lgkmcnt(0)
	v_mfma_f32_16x16x32_bf16 v[124:127], v[134:137], v[194:197], v[124:127]
	v_mfma_f32_16x16x32_bf16 v[120:123], v[142:145], v[194:197], v[120:123]
	v_mfma_f32_16x16x32_bf16 v[116:119], v[134:137], v[202:205], v[116:119]
	v_mfma_f32_16x16x32_bf16 v[112:115], v[142:145], v[202:205], v[112:115]
	v_mfma_f32_16x16x32_bf16 v[108:111], v[134:137], v[228:231], v[108:111]
	v_mfma_f32_16x16x32_bf16 v[104:107], v[142:145], v[228:231], v[104:107]
	v_mfma_f32_16x16x32_bf16 v[100:103], v[134:137], v[236:239], v[100:103]
	v_mfma_f32_16x16x32_bf16 v[96:99], v[142:145], v[236:239], v[96:99]
	v_mfma_f32_16x16x32_bf16 v[124:127], v[138:141], v[198:201], v[124:127]
	v_mfma_f32_16x16x32_bf16 v[120:123], v[146:149], v[198:201], v[120:123]
	v_mfma_f32_16x16x32_bf16 v[116:119], v[138:141], v[224:227], v[116:119]
	v_mfma_f32_16x16x32_bf16 v[112:115], v[146:149], v[224:227], v[112:115]
	v_mfma_f32_16x16x32_bf16 v[108:111], v[138:141], v[232:235], v[108:111]
	v_mfma_f32_16x16x32_bf16 v[104:107], v[146:149], v[232:235], v[104:107]
	v_mfma_f32_16x16x32_bf16 v[100:103], v[138:141], v[240:243], v[100:103]
	v_mfma_f32_16x16x32_bf16 v[96:99], v[146:149], v[240:243], v[96:99]
	s_setprio 0
	s_setprio 1
	v_mfma_f32_16x16x32_bf16 v[92:95], v[150:153], v[194:197], v[92:95]
	v_mfma_f32_16x16x32_bf16 v[88:91], v[174:177], v[194:197], v[88:91]
	v_mfma_f32_16x16x32_bf16 v[84:87], v[150:153], v[202:205], v[84:87]
	v_mfma_f32_16x16x32_bf16 v[80:83], v[174:177], v[202:205], v[80:83]
	v_mfma_f32_16x16x32_bf16 v[76:79], v[150:153], v[228:231], v[76:79]
	v_mfma_f32_16x16x32_bf16 v[72:75], v[174:177], v[228:231], v[72:75]
	v_mfma_f32_16x16x32_bf16 v[68:71], v[150:153], v[236:239], v[68:71]
	v_mfma_f32_16x16x32_bf16 v[64:67], v[174:177], v[236:239], v[64:67]
	v_mfma_f32_16x16x32_bf16 v[92:95], v[154:157], v[198:201], v[92:95]
	v_mfma_f32_16x16x32_bf16 v[88:91], v[190:193], v[198:201], v[88:91]
	v_mfma_f32_16x16x32_bf16 v[84:87], v[154:157], v[224:227], v[84:87]
	v_mfma_f32_16x16x32_bf16 v[80:83], v[190:193], v[224:227], v[80:83]
	v_mfma_f32_16x16x32_bf16 v[76:79], v[154:157], v[232:235], v[76:79]
	v_mfma_f32_16x16x32_bf16 v[72:75], v[190:193], v[232:235], v[72:75]
	v_mfma_f32_16x16x32_bf16 v[68:71], v[154:157], v[240:243], v[68:71]
	v_mfma_f32_16x16x32_bf16 v[64:67], v[190:193], v[240:243], v[64:67]
	s_setprio 2
	s_barrier
	s_add_i32 s27, s58, s10
	v_lshl_add_u64 v[178:179], v[158:159], 0, v[164:165]
	s_mov_b32 m0, s27
	ds_read_b128 v[194:197], v188 offset:16384
	ds_read_b128 v[198:201], v188 offset:17408
	ds_read_b128 v[202:205], v188 offset:18432
	ds_read_b128 v[224:227], v188 offset:19456
	ds_read_b128 v[228:231], v188 offset:20480
	ds_read_b128 v[232:235], v188 offset:21504
	ds_read_b128 v[236:239], v188 offset:22528
	ds_read_b128 v[240:243], v188 offset:23552
	global_load_lds_dwordx4 v[178:179], off
	v_lshl_add_u64 v[212:213], v[158:159], 0, v[168:169]
	s_add_i32 m0, s27, 0x2000
	v_lshl_add_u64 v[158:159], v[158:159], 0, s[96:97]
	s_add_i32 s19, s19, s10
	global_load_lds_dwordx4 v[212:213], off
	v_lshl_add_u64 v[218:219], v[158:159], 0, v[164:165]
	s_mov_b32 m0, s19
	v_lshl_add_u64 v[158:159], v[158:159], 0, v[168:169]
	global_load_lds_dwordx4 v[218:219], off
	s_add_i32 m0, s19, 0x2000
	v_lshl_add_u64 v[244:245], s[38:39], 0, v[162:163]
	global_load_lds_dwordx4 v[158:159], off
	s_mov_b32 m0, s11
	v_lshl_add_u64 v[246:247], s[38:39], 0, v[166:167]
	global_load_lds_dwordx4 v[244:245], off
	s_mov_b32 m0, s20
	s_nop 0
	global_load_lds_dwordx4 v[246:247], off
	s_waitcnt vmcnt(8)
	s_waitcnt lgkmcnt(0)
	s_barrier
; #define PG8_STAGE(bufoff, gbase, voff) do { _Pragma("unroll") for (int _i = 0; _i < 2; ++_i) \
;         __builtin_amdgcn_global_load_lds((const unsigned*)((const char*)(gbase) + (voff)[_i]), (LAS unsigned*)(lds + (bufoff) + ldsw + _i * 8192), 16, 0, 0); } while (0)
; #define PG8_LDA(dst, b, h) do { _Pragma("unroll") for (int m = 0; m < 4; ++m) _Pragma("unroll") for (int k = 0; k < 2; ++k) dst[m][k] = *(const LAS bf16x8*)(lds + PG8_SA(b, h) + aoff + m * 2048 + k * 1024); } while (0)
; #define PG8_LDB(dst, b, h) do { _Pragma("unroll") for (int n = 0; n < 2; ++n) _Pragma("unroll") for (int k = 0; k < 2; ++k) dst[n][k] = *(const LAS bf16x8*)(lds + PG8_SB(b, h) + boff + n * 2048 + k * 1024); } while (0)
; #define PG8_MMA(ai, bj, At, Bt) do { __builtin_amdgcn_s_setprio(1); _Pragma("unroll") for (int m = 0; m < 4; ++m) _Pragma("unroll") for (int n = 0; n < 2; ++n) _Pragma("unroll") for (int k = 0; k < 2; ++k) \
;         acc[ai][bj][m][n] = __builtin_amdgcn_mfma_f32_16x16x32_bf16(Bt[n][k], At[m][k], acc[ai][bj][m][n], 0, 0, 0); __builtin_amdgcn_s_setprio(0); } while (0)
; #define PG8_WAIT_V(n) asm volatile("s_waitcnt vmcnt(" #n ")" ::: "memory")
; #define PG8_WAIT_L(n) asm volatile("s_waitcnt lgkmcnt(" #n ")" ::: "memory")
; #define PG8_BAR __builtin_amdgcn_s_barrier()
; #define PG8_SCHED __builtin_amdgcn_sched_barrier(0)
;     ...
;             PG8_WAIT_V(8); PG8_WAIT_L(0); PG8_BAR; PG8_MMA(1, 0, At, B0); PG8_MMA(1, 1, At, B1); PG8_BAR; PG8_SCHED;
;             PG8_LDB(B0, 1, 0); PG8_LDB(B1, 1, 1); PG8_SCHED; PG8_LDA(At, 1, 0); PG8_STAGE(PG8_SA(0, 1), a2 + hstepA, voffA);
;             PG8_WAIT_V(8); PG8_WAIT_L(0); PG8_BAR; PG8_MMA(0, 0, At, B0); PG8_MMA(0, 1, At, B1); PG8_BAR; PG8_SCHED;
	s_setprio 1
	s_waitcnt lgkmcnt(0)
	v_mfma_f32_16x16x32_bf16 v[60:63], v[134:137], v[194:197], v[60:63]
	v_mfma_f32_16x16x32_bf16 v[56:59], v[142:145], v[194:197], v[56:59]
	v_mfma_f32_16x16x32_bf16 v[52:55], v[134:137], v[202:205], v[52:55]
	v_mfma_f32_16x16x32_bf16 v[48:51], v[142:145], v[202:205], v[48:51]
	v_mfma_f32_16x16x32_bf16 v[44:47], v[134:137], v[228:231], v[44:47]
	v_mfma_f32_16x16x32_bf16 v[40:43], v[142:145], v[228:231], v[40:43]
	v_mfma_f32_16x16x32_bf16 v[36:39], v[134:137], v[236:239], v[36:39]
	v_mfma_f32_16x16x32_bf16 v[32:35], v[142:145], v[236:239], v[32:35]
	v_mfma_f32_16x16x32_bf16 v[60:63], v[138:141], v[198:201], v[60:63]
	v_mfma_f32_16x16x32_bf16 v[56:59], v[146:149], v[198:201], v[56:59]
	v_mfma_f32_16x16x32_bf16 v[52:55], v[138:141], v[224:227], v[52:55]
	v_mfma_f32_16x16x32_bf16 v[48:51], v[146:149], v[224:227], v[48:51]
	v_mfma_f32_16x16x32_bf16 v[44:47], v[138:141], v[232:235], v[44:47]
	v_mfma_f32_16x16x32_bf16 v[40:43], v[146:149], v[232:235], v[40:43]
	v_mfma_f32_16x16x32_bf16 v[36:39], v[138:141], v[240:243], v[36:39]
	v_mfma_f32_16x16x32_bf16 v[32:35], v[146:149], v[240:243], v[32:35]
	s_setprio 0
	s_setprio 1
	v_mfma_f32_16x16x32_bf16 v[28:31], v[150:153], v[194:197], v[28:31]
	v_mfma_f32_16x16x32_bf16 v[24:27], v[174:177], v[194:197], v[24:27]
	v_mfma_f32_16x16x32_bf16 v[20:23], v[150:153], v[202:205], v[20:23]
	v_mfma_f32_16x16x32_bf16 v[16:19], v[174:177], v[202:205], v[16:19]
	v_mfma_f32_16x16x32_bf16 v[12:15], v[150:153], v[228:231], v[12:15]
	v_mfma_f32_16x16x32_bf16 v[8:11], v[174:177], v[228:231], v[8:11]
	v_mfma_f32_16x16x32_bf16 v[4:7], v[150:153], v[236:239], v[4:7]
	v_mfma_f32_16x16x32_bf16 v[0:3], v[174:177], v[236:239], v[0:3]
	v_mfma_f32_16x16x32_bf16 v[28:31], v[154:157], v[198:201], v[28:31]
	v_mfma_f32_16x16x32_bf16 v[24:27], v[190:193], v[198:201], v[24:27]
	v_mfma_f32_16x16x32_bf16 v[20:23], v[154:157], v[224:227], v[20:23]
	v_mfma_f32_16x16x32_bf16 v[16:19], v[190:193], v[224:227], v[16:19]
	v_mfma_f32_16x16x32_bf16 v[12:15], v[154:157], v[232:235], v[12:15]
	v_mfma_f32_16x16x32_bf16 v[8:11], v[190:193], v[232:235], v[8:11]
	v_mfma_f32_16x16x32_bf16 v[4:7], v[154:157], v[240:243], v[4:7]
	v_mfma_f32_16x16x32_bf16 v[0:3], v[190:193], v[240:243], v[0:3]
	s_setprio 2
	s_barrier
	s_add_i32 s19, 0, 0x18000
	s_add_i32 s27, 0, 0x1c000
	v_add_u32_e32 v146, s19, v181
	v_add_u32_e32 v182, s27, v181
	ds_read_b128 v[134:137], v146
	ds_read_b128 v[138:141], v146 offset:1024
	ds_read_b128 v[142:145], v146 offset:2048
	ds_read_b128 v[146:149], v146 offset:3072
	ds_read_b128 v[150:153], v182
	ds_read_b128 v[154:157], v182 offset:1024
	ds_read_b128 v[174:177], v182 offset:2048
	ds_read_b128 v[190:193], v182 offset:3072
	s_add_u32 s38, s38, s96
	s_addc_u32 s39, s39, 0
	s_mov_b32 m0, s48
	v_lshl_add_u64 v[248:249], s[38:39], 0, v[162:163]
	ds_read_b128 v[194:197], v188 offset:32768
	ds_read_b128 v[198:201], v188 offset:33792
	ds_read_b128 v[202:205], v188 offset:34816
	ds_read_b128 v[224:227], v188 offset:35840
	ds_read_b128 v[228:231], v188 offset:36864
	ds_read_b128 v[232:235], v188 offset:37888
	ds_read_b128 v[236:239], v188 offset:38912
	ds_read_b128 v[240:243], v188 offset:39936
	global_load_lds_dwordx4 v[248:249], off
	v_lshl_add_u64 v[248:249], s[38:39], 0, v[166:167]
	s_mov_b32 m0, s49
	s_nop 0
	global_load_lds_dwordx4 v[248:249], off
	s_waitcnt vmcnt(8)
	s_waitcnt lgkmcnt(0)
	s_barrier
	s_setprio 1
	s_waitcnt lgkmcnt(0)
	v_mfma_f32_16x16x32_bf16 v[124:127], v[134:137], v[194:197], v[124:127]
	v_mfma_f32_16x16x32_bf16 v[120:123], v[142:145], v[194:197], v[120:123]
	v_mfma_f32_16x16x32_bf16 v[116:119], v[134:137], v[202:205], v[116:119]
	v_mfma_f32_16x16x32_bf16 v[112:115], v[142:145], v[202:205], v[112:115]
	v_mfma_f32_16x16x32_bf16 v[108:111], v[134:137], v[228:231], v[108:111]
	v_mfma_f32_16x16x32_bf16 v[104:107], v[142:145], v[228:231], v[104:107]
	v_mfma_f32_16x16x32_bf16 v[100:103], v[134:137], v[236:239], v[100:103]
	v_mfma_f32_16x16x32_bf16 v[96:99], v[142:145], v[236:239], v[96:99]
	v_mfma_f32_16x16x32_bf16 v[124:127], v[138:141], v[198:201], v[124:127]
	v_mfma_f32_16x16x32_bf16 v[120:123], v[146:149], v[198:201], v[120:123]
	v_mfma_f32_16x16x32_bf16 v[116:119], v[138:141], v[224:227], v[116:119]
	v_mfma_f32_16x16x32_bf16 v[112:115], v[146:149], v[224:227], v[112:115]
	v_mfma_f32_16x16x32_bf16 v[108:111], v[138:141], v[232:235], v[108:111]
	v_mfma_f32_16x16x32_bf16 v[104:107], v[146:149], v[232:235], v[104:107]
	v_mfma_f32_16x16x32_bf16 v[100:103], v[138:141], v[240:243], v[100:103]
	v_mfma_f32_16x16x32_bf16 v[96:99], v[146:149], v[240:243], v[96:99]
	s_setprio 0
	s_setprio 1
	v_mfma_f32_16x16x32_bf16 v[92:95], v[150:153], v[194:197], v[92:95]
	v_mfma_f32_16x16x32_bf16 v[88:91], v[174:177], v[194:197], v[88:91]
	v_mfma_f32_16x16x32_bf16 v[84:87], v[150:153], v[202:205], v[84:87]
	v_mfma_f32_16x16x32_bf16 v[80:83], v[174:177], v[202:205], v[80:83]
	v_mfma_f32_16x16x32_bf16 v[76:79], v[150:153], v[228:231], v[76:79]
	v_mfma_f32_16x16x32_bf16 v[72:75], v[174:177], v[228:231], v[72:75]
	v_mfma_f32_16x16x32_bf16 v[68:71], v[150:153], v[236:239], v[68:71]
	v_mfma_f32_16x16x32_bf16 v[64:67], v[174:177], v[236:239], v[64:67]
	v_mfma_f32_16x16x32_bf16 v[92:95], v[154:157], v[198:201], v[92:95]
	v_mfma_f32_16x16x32_bf16 v[88:91], v[190:193], v[198:201], v[88:91]
	v_mfma_f32_16x16x32_bf16 v[84:87], v[154:157], v[224:227], v[84:87]
	v_mfma_f32_16x16x32_bf16 v[80:83], v[190:193], v[224:227], v[80:83]
	v_mfma_f32_16x16x32_bf16 v[76:79], v[154:157], v[232:235], v[76:79]
	v_mfma_f32_16x16x32_bf16 v[72:75], v[190:193], v[232:235], v[72:75]
	v_mfma_f32_16x16x32_bf16 v[68:71], v[154:157], v[240:243], v[68:71]
	v_mfma_f32_16x16x32_bf16 v[64:67], v[190:193], v[240:243], v[64:67]
	s_setprio 2
	s_barrier
; #define PG8_STAGE(bufoff, gbase, voff) do { _Pragma("unroll") for (int _i = 0; _i < 2; ++_i) \
;         __builtin_amdgcn_global_load_lds((const unsigned*)((const char*)(gbase) + (voff)[_i]), (LAS unsigned*)(lds + (bufoff) + ldsw + _i * 8192), 16, 0, 0); } while (0)
; #define PG8_LDA(dst, b, h) do { _Pragma("unroll") for (int m = 0; m < 4; ++m) _Pragma("unroll") for (int k = 0; k < 2; ++k) dst[m][k] = *(const LAS bf16x8*)(lds + PG8_SA(b, h) + aoff + m * 2048 + k * 1024); } while (0)
; #define PG8_MMA(ai, bj, At, Bt) do { __builtin_amdgcn_s_setprio(1); _Pragma("unroll") for (int m = 0; m < 4; ++m) _Pragma("unroll") for (int n = 0; n < 2; ++n) _Pragma("unroll") for (int k = 0; k < 2; ++k) \
;         acc[ai][bj][m][n] = __builtin_amdgcn_mfma_f32_16x16x32_bf16(Bt[n][k], At[m][k], acc[ai][bj][m][n], 0, 0, 0); __builtin_amdgcn_s_setprio(0); } while (0)
; #define PG8_WAIT_V(n) asm volatile("s_waitcnt vmcnt(" #n ")" ::: "memory")
; #define PG8_WAIT_L(n) asm volatile("s_waitcnt lgkmcnt(" #n ")" ::: "memory")
; #define PG8_BAR __builtin_amdgcn_s_barrier()
; #define PG8_SCHED __builtin_amdgcn_sched_barrier(0)
;     ...
;             PG8_LDA(At, 1, 1); PG8_STAGE(PG8_SB(1, 0), b3, voffB); PG8_STAGE(PG8_SB(1, 1), b3 + hstepB, voffB); PG8_STAGE(PG8_SA(1, 0), a3, voffA);
;             PG8_WAIT_V(8); PG8_WAIT_L(0); PG8_BAR; PG8_MMA(1, 0, At, B0); PG8_MMA(1, 1, At, B1); PG8_BAR; PG8_SCHED;
;         }
;         if (wr == 0) PG8_BAR;
	s_add_i32 s19, s19, s10
	v_lshl_add_u64 v[178:179], v[178:179], 0, s[70:71]
	s_mov_b32 m0, s19
	ds_read_b128 v[194:197], v188 offset:49152
	ds_read_b128 v[198:201], v188 offset:50176
	ds_read_b128 v[202:205], v188 offset:51200
	ds_read_b128 v[224:227], v188 offset:52224
	ds_read_b128 v[228:231], v188 offset:53248
	ds_read_b128 v[232:235], v188 offset:54272
	ds_read_b128 v[236:239], v188 offset:55296
	ds_read_b128 v[240:243], v188 offset:56320
	global_load_lds_dwordx4 v[178:179], off
	v_lshl_add_u64 v[178:179], v[212:213], 0, s[70:71]
	s_add_i32 m0, s19, 0x2000
	s_add_i32 s19, s27, s10
	global_load_lds_dwordx4 v[178:179], off
	v_lshl_add_u64 v[178:179], v[218:219], 0, s[70:71]
	s_mov_b32 m0, s19
	v_lshl_add_u64 v[158:159], v[158:159], 0, s[70:71]
	global_load_lds_dwordx4 v[178:179], off
	s_add_i32 m0, s19, 0x2000
	s_nop 0
	global_load_lds_dwordx4 v[158:159], off
	v_lshl_add_u64 v[158:159], v[244:245], 0, s[70:71]
	s_mov_b32 m0, s62
	s_nop 0
	global_load_lds_dwordx4 v[158:159], off
	v_lshl_add_u64 v[158:159], v[246:247], 0, s[70:71]
	s_mov_b32 m0, s63
	s_nop 0
	global_load_lds_dwordx4 v[158:159], off
	s_waitcnt vmcnt(8)
	s_waitcnt lgkmcnt(0)
	s_barrier
	s_setprio 1
	s_waitcnt lgkmcnt(0)
	v_mfma_f32_16x16x32_bf16 v[60:63], v[134:137], v[194:197], v[60:63]
	v_mfma_f32_16x16x32_bf16 v[56:59], v[142:145], v[194:197], v[56:59]
	v_mfma_f32_16x16x32_bf16 v[52:55], v[134:137], v[202:205], v[52:55]
	v_mfma_f32_16x16x32_bf16 v[48:51], v[142:145], v[202:205], v[48:51]
	v_mfma_f32_16x16x32_bf16 v[44:47], v[134:137], v[228:231], v[44:47]
	v_mfma_f32_16x16x32_bf16 v[40:43], v[142:145], v[228:231], v[40:43]
	v_mfma_f32_16x16x32_bf16 v[36:39], v[134:137], v[236:239], v[36:39]
	v_mfma_f32_16x16x32_bf16 v[32:35], v[142:145], v[236:239], v[32:35]
	v_mfma_f32_16x16x32_bf16 v[60:63], v[138:141], v[198:201], v[60:63]
	v_mfma_f32_16x16x32_bf16 v[56:59], v[146:149], v[198:201], v[56:59]
	v_mfma_f32_16x16x32_bf16 v[52:55], v[138:141], v[224:227], v[52:55]
	v_mfma_f32_16x16x32_bf16 v[48:51], v[146:149], v[224:227], v[48:51]
	v_mfma_f32_16x16x32_bf16 v[44:47], v[138:141], v[232:235], v[44:47]
	v_mfma_f32_16x16x32_bf16 v[40:43], v[146:149], v[232:235], v[40:43]
	v_mfma_f32_16x16x32_bf16 v[36:39], v[138:141], v[240:243], v[36:39]
	v_mfma_f32_16x16x32_bf16 v[32:35], v[146:149], v[240:243], v[32:35]
	s_setprio 0
	s_setprio 1
	v_mfma_f32_16x16x32_bf16 v[28:31], v[150:153], v[194:197], v[28:31]
	v_mfma_f32_16x16x32_bf16 v[24:27], v[174:177], v[194:197], v[24:27]
	v_mfma_f32_16x16x32_bf16 v[20:23], v[150:153], v[202:205], v[20:23]
	v_mfma_f32_16x16x32_bf16 v[16:19], v[174:177], v[202:205], v[16:19]
	v_mfma_f32_16x16x32_bf16 v[12:15], v[150:153], v[228:231], v[12:15]
	v_mfma_f32_16x16x32_bf16 v[8:11], v[174:177], v[228:231], v[8:11]
	v_mfma_f32_16x16x32_bf16 v[4:7], v[150:153], v[236:239], v[4:7]
	v_mfma_f32_16x16x32_bf16 v[0:3], v[174:177], v[236:239], v[0:3]
	v_mfma_f32_16x16x32_bf16 v[28:31], v[154:157], v[198:201], v[28:31]
	v_mfma_f32_16x16x32_bf16 v[24:27], v[190:193], v[198:201], v[24:27]
	v_mfma_f32_16x16x32_bf16 v[20:23], v[154:157], v[224:227], v[20:23]
	v_mfma_f32_16x16x32_bf16 v[16:19], v[190:193], v[224:227], v[16:19]
	v_mfma_f32_16x16x32_bf16 v[12:15], v[154:157], v[232:235], v[12:15]
	v_mfma_f32_16x16x32_bf16 v[8:11], v[190:193], v[232:235], v[8:11]
	v_mfma_f32_16x16x32_bf16 v[4:7], v[154:157], v[240:243], v[4:7]
	v_mfma_f32_16x16x32_bf16 v[0:3], v[190:193], v[240:243], v[0:3]
	s_setprio 2
	s_barrier
	s_add_u32 s0, s0, 0x100
	s_addc_u32 s1, s1, 0
	v_lshl_add_u64 v[130:131], v[130:131], 0, s[94:95]
	v_lshl_add_u64 v[128:129], v[128:129], 0, s[94:95]
	s_cmp_ge_u32 s57, s16
	s_mov_b32 s38, s57
	s_cbranch_scc0 .LBB0_318
	v_readlane_b32 s0, v254, 50
	v_readlane_b32 s1, v254, 51
	s_and_b64 vcc, exec, s[0:1]
	s_mov_b32 s68, 0x134000
	s_mov_b32 s69, 0x160000
	s_cbranch_vccz .LBB0_321
	s_barrier

; #define PG8_STAGE(bufoff, gbase, voff) do { _Pragma("unroll") for (int _i = 0; _i < 2; ++_i) \
;         __builtin_amdgcn_global_load_lds((const unsigned*)((const char*)(gbase) + (voff)[_i]), (LAS unsigned*)(lds + (bufoff) + ldsw + _i * 8192), 16, 0, 0); } while (0)
; #define PG8_LDA(dst, b, h) do { _Pragma("unroll") for (int m = 0; m < 4; ++m) _Pragma("unroll") for (int k = 0; k < 2; ++k) dst[m][k] = *(const LAS bf16x8*)(lds + PG8_SA(b, h) + aoff + m * 2048 + k * 1024); } while (0)
; #define PG8_LDB(dst, b, h) do { _Pragma("unroll") for (int n = 0; n < 2; ++n) _Pragma("unroll") for (int k = 0; k < 2; ++k) dst[n][k] = *(const LAS bf16x8*)(lds + PG8_SB(b, h) + boff + n * 2048 + k * 1024); } while (0)
; #define PG8_MMA(ai, bj, At, Bt) do { __builtin_amdgcn_s_setprio(1); _Pragma("unroll") for (int m = 0; m < 4; ++m) _Pragma("unroll") for (int n = 0; n < 2; ++n) _Pragma("unroll") for (int k = 0; k < 2; ++k) \
;         acc[ai][bj][m][n] = __builtin_amdgcn_mfma_f32_16x16x32_bf16(Bt[n][k], At[m][k], acc[ai][bj][m][n], 0, 0, 0); __builtin_amdgcn_s_setprio(0); } while (0)
; #define PG8_WAIT_V(n) asm volatile("s_waitcnt vmcnt(" #n ")" ::: "memory")
; #define PG8_WAIT_L(n) asm volatile("s_waitcnt lgkmcnt(" #n ")" ::: "memory")
; #define PG8_BAR __builtin_amdgcn_s_barrier()
; #define PG8_SCHED __builtin_amdgcn_sched_barrier(0)
;     ...
;         for (int t = 0; t < nt; t += 2) {
;             const bool last = (t == nt - 2);
;             const char* a1 = cA + (size_t)(t + 1) * kstep;
;             const char* a2 = last ? nA : cA + (size_t)(t + 2) * kstep; const char* b2 = last ? nB : cB + (size_t)(t + 2) * kstep;
;             const char* a3 = a2 + kstep; const char* b3 = b2 + kstep;
;             PG8_LDB(B0, 0, 0); PG8_LDB(B1, 0, 1); PG8_SCHED; PG8_LDA(At, 0, 0); PG8_STAGE(PG8_SA(1, 1), a1 + hstepA, voffA);
;             PG8_WAIT_V(8); PG8_WAIT_L(0); PG8_BAR; PG8_MMA(0, 0, At, B0); PG8_MMA(0, 1, At, B1); PG8_BAR; PG8_SCHED;
;             PG8_LDA(At, 0, 1); PG8_STAGE(PG8_SB(0, 0), b2, voffB); PG8_STAGE(PG8_SB(0, 1), b2 + hstepB, voffB); PG8_STAGE(PG8_SA(0, 0), a2, voffA);
;             PG8_WAIT_V(8); PG8_WAIT_L(0); PG8_BAR; PG8_MMA(1, 0, At, B0); PG8_MMA(1, 1, At, B1); PG8_BAR; PG8_SCHED;
.LBB0_416:
	s_add_i32 s8, s2, 2
	s_add_u32 s9, s52, s0
	s_addc_u32 s3, s53, s1
	s_add_i32 s26, 0, 0x10000
	s_cmp_eq_u32 s65, s2
	s_cselect_b32 s3, s6, s3
	s_cselect_b32 s2, s7, s9
	v_add_u32_e32 v153, s26, v148
	s_cselect_b64 vcc, -1, 0
	s_add_i32 s9, 0, 0x14000
	v_lshl_add_u64 v[170:171], v[128:129], 0, s[0:1]
	ds_read_b128 v[154:157], v153
	ds_read_b128 v[158:161], v153 offset:1024
	ds_read_b128 v[162:165], v153 offset:2048
	ds_read_b128 v[166:169], v153 offset:3072
	v_add_u32_e32 v153, s9, v148
	v_cndmask_b32_e32 v205, v171, v151, vcc
	v_cndmask_b32_e32 v204, v170, v152, vcc
	ds_read_b128 v[170:173], v153
	ds_read_b128 v[174:177], v153 offset:1024
	ds_read_b128 v[178:181], v153 offset:2048
	ds_read_b128 v[188:191], v153 offset:3072
	v_lshl_add_u64 v[244:245], s[52:53], 0, v[146:147]
	s_add_i32 m0, s41, 0xc000
	ds_read_b128 v[192:195], v149
	ds_read_b128 v[196:199], v149 offset:1024
	ds_read_b128 v[200:203], v149 offset:2048
	ds_read_b128 v[224:227], v149 offset:3072
	ds_read_b128 v[228:231], v149 offset:4096
	ds_read_b128 v[232:235], v149 offset:5120
	ds_read_b128 v[236:239], v149 offset:6144
	ds_read_b128 v[240:243], v149 offset:7168
	global_load_lds_dwordx4 v[244:245], off
	v_lshl_add_u64 v[244:245], s[52:53], 0, v[144:145]
	s_add_i32 m0, s41, 0xe000
	s_nop 0
	global_load_lds_dwordx4 v[244:245], off
	s_waitcnt vmcnt(8)
	s_waitcnt lgkmcnt(0)
	s_barrier
	s_setprio 1
	s_waitcnt lgkmcnt(0)
	v_mfma_f32_16x16x32_bf16 v[124:127], v[154:157], v[192:195], v[124:127]
	v_mfma_f32_16x16x32_bf16 v[120:123], v[162:165], v[192:195], v[120:123]
	v_mfma_f32_16x16x32_bf16 v[116:119], v[154:157], v[200:203], v[116:119]
	v_mfma_f32_16x16x32_bf16 v[112:115], v[162:165], v[200:203], v[112:115]
	v_mfma_f32_16x16x32_bf16 v[108:111], v[154:157], v[228:231], v[108:111]
	v_mfma_f32_16x16x32_bf16 v[104:107], v[162:165], v[228:231], v[104:107]
	v_mfma_f32_16x16x32_bf16 v[100:103], v[154:157], v[236:239], v[100:103]
	v_mfma_f32_16x16x32_bf16 v[96:99], v[162:165], v[236:239], v[96:99]
	v_mfma_f32_16x16x32_bf16 v[124:127], v[158:161], v[196:199], v[124:127]
	v_mfma_f32_16x16x32_bf16 v[120:123], v[166:169], v[196:199], v[120:123]
	v_mfma_f32_16x16x32_bf16 v[116:119], v[158:161], v[224:227], v[116:119]
	v_mfma_f32_16x16x32_bf16 v[112:115], v[166:169], v[224:227], v[112:115]
	v_mfma_f32_16x16x32_bf16 v[108:111], v[158:161], v[232:235], v[108:111]
	v_mfma_f32_16x16x32_bf16 v[104:107], v[166:169], v[232:235], v[104:107]
	v_mfma_f32_16x16x32_bf16 v[100:103], v[158:161], v[240:243], v[100:103]
	v_mfma_f32_16x16x32_bf16 v[96:99], v[166:169], v[240:243], v[96:99]
	s_setprio 0
	s_setprio 1
	v_mfma_f32_16x16x32_bf16 v[92:95], v[170:173], v[192:195], v[92:95]
	v_mfma_f32_16x16x32_bf16 v[88:91], v[178:181], v[192:195], v[88:91]
	v_mfma_f32_16x16x32_bf16 v[84:87], v[170:173], v[200:203], v[84:87]
	v_mfma_f32_16x16x32_bf16 v[80:83], v[178:181], v[200:203], v[80:83]
	v_mfma_f32_16x16x32_bf16 v[76:79], v[170:173], v[228:231], v[76:79]
	v_mfma_f32_16x16x32_bf16 v[72:75], v[178:181], v[228:231], v[72:75]
	v_mfma_f32_16x16x32_bf16 v[68:71], v[170:173], v[236:239], v[68:71]
	v_mfma_f32_16x16x32_bf16 v[64:67], v[178:181], v[236:239], v[64:67]
	v_mfma_f32_16x16x32_bf16 v[92:95], v[174:177], v[196:199], v[92:95]
	v_mfma_f32_16x16x32_bf16 v[88:91], v[188:191], v[196:199], v[88:91]
	v_mfma_f32_16x16x32_bf16 v[84:87], v[174:177], v[224:227], v[84:87]
	v_mfma_f32_16x16x32_bf16 v[80:83], v[188:191], v[224:227], v[80:83]
	v_mfma_f32_16x16x32_bf16 v[76:79], v[174:177], v[232:235], v[76:79]
	v_mfma_f32_16x16x32_bf16 v[72:75], v[188:191], v[232:235], v[72:75]
	v_mfma_f32_16x16x32_bf16 v[68:71], v[174:177], v[240:243], v[68:71]
	v_mfma_f32_16x16x32_bf16 v[64:67], v[188:191], v[240:243], v[64:67]
	s_setprio 2
	s_barrier
	s_add_i32 s26, s26, s40
	v_lshl_add_u64 v[244:245], v[204:205], 0, v[132:133]
	s_mov_b32 m0, s26
	ds_read_b128 v[192:195], v149 offset:16384
	ds_read_b128 v[196:199], v149 offset:17408
	ds_read_b128 v[200:203], v149 offset:18432
	ds_read_b128 v[224:227], v149 offset:19456
	ds_read_b128 v[228:231], v149 offset:20480
	ds_read_b128 v[232:235], v149 offset:21504
	ds_read_b128 v[236:239], v149 offset:22528
	ds_read_b128 v[240:243], v149 offset:23552
	global_load_lds_dwordx4 v[244:245], off
	v_lshl_add_u64 v[246:247], v[204:205], 0, v[136:137]
	s_add_i32 m0, s26, 0x2000
	v_lshl_add_u64 v[204:205], v[204:205], 0, s[58:59]
	s_add_i32 s9, s9, s40
	global_load_lds_dwordx4 v[246:247], off
	v_lshl_add_u64 v[248:249], v[204:205], 0, v[132:133]
	s_mov_b32 m0, s9
	v_lshl_add_u64 v[204:205], v[204:205], 0, v[136:137]
	global_load_lds_dwordx4 v[248:249], off
	s_add_i32 m0, s9, 0x2000
	v_lshl_add_u64 v[250:251], s[2:3], 0, v[130:131]
	global_load_lds_dwordx4 v[204:205], off
	s_mov_b32 m0, s41
	v_lshl_add_u64 v[218:219], s[2:3], 0, v[134:135]
	global_load_lds_dwordx4 v[250:251], off
	s_mov_b32 m0, s49
	s_nop 0
	global_load_lds_dwordx4 v[218:219], off
	s_waitcnt vmcnt(8)
	s_waitcnt lgkmcnt(0)
	s_barrier
; #define PG8_STAGE(bufoff, gbase, voff) do { _Pragma("unroll") for (int _i = 0; _i < 2; ++_i) \
;         __builtin_amdgcn_global_load_lds((const unsigned*)((const char*)(gbase) + (voff)[_i]), (LAS unsigned*)(lds + (bufoff) + ldsw + _i * 8192), 16, 0, 0); } while (0)
; #define PG8_LDA(dst, b, h) do { _Pragma("unroll") for (int m = 0; m < 4; ++m) _Pragma("unroll") for (int k = 0; k < 2; ++k) dst[m][k] = *(const LAS bf16x8*)(lds + PG8_SA(b, h) + aoff + m * 2048 + k * 1024); } while (0)
; #define PG8_LDB(dst, b, h) do { _Pragma("unroll") for (int n = 0; n < 2; ++n) _Pragma("unroll") for (int k = 0; k < 2; ++k) dst[n][k] = *(const LAS bf16x8*)(lds + PG8_SB(b, h) + boff + n * 2048 + k * 1024); } while (0)
; #define PG8_MMA(ai, bj, At, Bt) do { __builtin_amdgcn_s_setprio(1); _Pragma("unroll") for (int m = 0; m < 4; ++m) _Pragma("unroll") for (int n = 0; n < 2; ++n) _Pragma("unroll") for (int k = 0; k < 2; ++k) \
;         acc[ai][bj][m][n] = __builtin_amdgcn_mfma_f32_16x16x32_bf16(Bt[n][k], At[m][k], acc[ai][bj][m][n], 0, 0, 0); __builtin_amdgcn_s_setprio(0); } while (0)
; #define PG8_WAIT_V(n) asm volatile("s_waitcnt vmcnt(" #n ")" ::: "memory")
; #define PG8_WAIT_L(n) asm volatile("s_waitcnt lgkmcnt(" #n ")" ::: "memory")
; #define PG8_BAR __builtin_amdgcn_s_barrier()
; #define PG8_SCHED __builtin_amdgcn_sched_barrier(0)
;     ...
;             PG8_LDB(B0, 0, 0); PG8_LDB(B1, 0, 1); PG8_SCHED; PG8_LDA(At, 0, 0); PG8_STAGE(PG8_SA(1, 1), a1 + hstepA, voffA);
;             PG8_WAIT_V(8); PG8_WAIT_L(0); PG8_BAR; PG8_MMA(0, 0, At, B0); PG8_MMA(0, 1, At, B1); PG8_BAR; PG8_SCHED;
;             PG8_LDA(At, 0, 1); PG8_STAGE(PG8_SB(0, 0), b2, voffB); PG8_STAGE(PG8_SB(0, 1), b2 + hstepB, voffB); PG8_STAGE(PG8_SA(0, 0), a2, voffA);
;             PG8_WAIT_V(8); PG8_WAIT_L(0); PG8_BAR; PG8_MMA(1, 0, At, B0); PG8_MMA(1, 1, At, B1); PG8_BAR; PG8_SCHED;
;             PG8_LDB(B0, 1, 0); PG8_LDB(B1, 1, 1); PG8_SCHED; PG8_LDA(At, 1, 0); PG8_STAGE(PG8_SA(0, 1), a2 + hstepA, voffA);
;             PG8_WAIT_V(8); PG8_WAIT_L(0); PG8_BAR; PG8_MMA(0, 0, At, B0); PG8_MMA(0, 1, At, B1); PG8_BAR; PG8_SCHED;
;             PG8_LDA(At, 1, 1); PG8_STAGE(PG8_SB(1, 0), b3, voffB); PG8_STAGE(PG8_SB(1, 1), b3 + hstepB, voffB); PG8_STAGE(PG8_SA(1, 0), a3, voffA);
;             PG8_WAIT_V(8); PG8_WAIT_L(0); PG8_BAR; PG8_MMA(1, 0, At, B0); PG8_MMA(1, 1, At, B1); PG8_BAR; PG8_SCHED;
	s_setprio 1
	s_waitcnt lgkmcnt(0)
	v_mfma_f32_16x16x32_bf16 v[60:63], v[154:157], v[192:195], v[60:63]
	v_mfma_f32_16x16x32_bf16 v[56:59], v[162:165], v[192:195], v[56:59]
	v_mfma_f32_16x16x32_bf16 v[52:55], v[154:157], v[200:203], v[52:55]
	v_mfma_f32_16x16x32_bf16 v[48:51], v[162:165], v[200:203], v[48:51]
	v_mfma_f32_16x16x32_bf16 v[44:47], v[154:157], v[228:231], v[44:47]
	v_mfma_f32_16x16x32_bf16 v[40:43], v[162:165], v[228:231], v[40:43]
	v_mfma_f32_16x16x32_bf16 v[36:39], v[154:157], v[236:239], v[36:39]
	v_mfma_f32_16x16x32_bf16 v[32:35], v[162:165], v[236:239], v[32:35]
	v_mfma_f32_16x16x32_bf16 v[60:63], v[158:161], v[196:199], v[60:63]
	v_mfma_f32_16x16x32_bf16 v[56:59], v[166:169], v[196:199], v[56:59]
	v_mfma_f32_16x16x32_bf16 v[52:55], v[158:161], v[224:227], v[52:55]
	v_mfma_f32_16x16x32_bf16 v[48:51], v[166:169], v[224:227], v[48:51]
	v_mfma_f32_16x16x32_bf16 v[44:47], v[158:161], v[232:235], v[44:47]
	v_mfma_f32_16x16x32_bf16 v[40:43], v[166:169], v[232:235], v[40:43]
	v_mfma_f32_16x16x32_bf16 v[36:39], v[158:161], v[240:243], v[36:39]
	v_mfma_f32_16x16x32_bf16 v[32:35], v[166:169], v[240:243], v[32:35]
	s_setprio 0
	s_setprio 1
	v_mfma_f32_16x16x32_bf16 v[28:31], v[170:173], v[192:195], v[28:31]
	v_mfma_f32_16x16x32_bf16 v[24:27], v[178:181], v[192:195], v[24:27]
	v_mfma_f32_16x16x32_bf16 v[20:23], v[170:173], v[200:203], v[20:23]
	v_mfma_f32_16x16x32_bf16 v[16:19], v[178:181], v[200:203], v[16:19]
	v_mfma_f32_16x16x32_bf16 v[12:15], v[170:173], v[228:231], v[12:15]
	v_mfma_f32_16x16x32_bf16 v[8:11], v[178:181], v[228:231], v[8:11]
	v_mfma_f32_16x16x32_bf16 v[4:7], v[170:173], v[236:239], v[4:7]
	v_mfma_f32_16x16x32_bf16 v[0:3], v[178:181], v[236:239], v[0:3]
	v_mfma_f32_16x16x32_bf16 v[28:31], v[174:177], v[196:199], v[28:31]
	v_mfma_f32_16x16x32_bf16 v[24:27], v[188:191], v[196:199], v[24:27]
	v_mfma_f32_16x16x32_bf16 v[20:23], v[174:177], v[224:227], v[20:23]
	v_mfma_f32_16x16x32_bf16 v[16:19], v[188:191], v[224:227], v[16:19]
	v_mfma_f32_16x16x32_bf16 v[12:15], v[174:177], v[232:235], v[12:15]
	v_mfma_f32_16x16x32_bf16 v[8:11], v[188:191], v[232:235], v[8:11]
	v_mfma_f32_16x16x32_bf16 v[4:7], v[174:177], v[240:243], v[4:7]
	v_mfma_f32_16x16x32_bf16 v[0:3], v[188:191], v[240:243], v[0:3]
	s_setprio 2
	s_barrier
	s_add_i32 s9, 0, 0x18000
	v_add_u32_e32 v153, s9, v148
	s_add_i32 s26, 0, 0x1c000
	ds_read_b128 v[154:157], v153
	ds_read_b128 v[158:161], v153 offset:1024
	ds_read_b128 v[162:165], v153 offset:2048
	ds_read_b128 v[166:169], v153 offset:3072
	v_add_u32_e32 v153, s26, v148
	ds_read_b128 v[170:173], v153
	ds_read_b128 v[174:177], v153 offset:1024
	ds_read_b128 v[178:181], v153 offset:2048
	ds_read_b128 v[188:191], v153 offset:3072
	s_add_u32 s2, s2, s58
	s_addc_u32 s3, s3, 0
	s_mov_b32 m0, s10
	v_lshl_add_u64 v[212:213], s[2:3], 0, v[130:131]
	ds_read_b128 v[192:195], v149 offset:32768
	ds_read_b128 v[196:199], v149 offset:33792
	ds_read_b128 v[200:203], v149 offset:34816
	ds_read_b128 v[224:227], v149 offset:35840
	ds_read_b128 v[228:231], v149 offset:36864
	ds_read_b128 v[232:235], v149 offset:37888
	ds_read_b128 v[236:239], v149 offset:38912
	ds_read_b128 v[240:243], v149 offset:39936
	global_load_lds_dwordx4 v[212:213], off
	v_lshl_add_u64 v[212:213], s[2:3], 0, v[134:135]
	s_mov_b32 m0, s11
	s_nop 0
	global_load_lds_dwordx4 v[212:213], off
	s_waitcnt vmcnt(8)
	s_waitcnt lgkmcnt(0)
	s_barrier
	s_setprio 1
	s_waitcnt lgkmcnt(0)
	v_mfma_f32_16x16x32_bf16 v[124:127], v[154:157], v[192:195], v[124:127]
	v_mfma_f32_16x16x32_bf16 v[120:123], v[162:165], v[192:195], v[120:123]
	v_mfma_f32_16x16x32_bf16 v[116:119], v[154:157], v[200:203], v[116:119]
	v_mfma_f32_16x16x32_bf16 v[112:115], v[162:165], v[200:203], v[112:115]
	v_mfma_f32_16x16x32_bf16 v[108:111], v[154:157], v[228:231], v[108:111]
	v_mfma_f32_16x16x32_bf16 v[104:107], v[162:165], v[228:231], v[104:107]
	v_mfma_f32_16x16x32_bf16 v[100:103], v[154:157], v[236:239], v[100:103]
	v_mfma_f32_16x16x32_bf16 v[96:99], v[162:165], v[236:239], v[96:99]
	v_mfma_f32_16x16x32_bf16 v[124:127], v[158:161], v[196:199], v[124:127]
	v_mfma_f32_16x16x32_bf16 v[120:123], v[166:169], v[196:199], v[120:123]
	v_mfma_f32_16x16x32_bf16 v[116:119], v[158:161], v[224:227], v[116:119]
	v_mfma_f32_16x16x32_bf16 v[112:115], v[166:169], v[224:227], v[112:115]
	v_mfma_f32_16x16x32_bf16 v[108:111], v[158:161], v[232:235], v[108:111]
	v_mfma_f32_16x16x32_bf16 v[104:107], v[166:169], v[232:235], v[104:107]
	v_mfma_f32_16x16x32_bf16 v[100:103], v[158:161], v[240:243], v[100:103]
	v_mfma_f32_16x16x32_bf16 v[96:99], v[166:169], v[240:243], v[96:99]
	s_setprio 0
	s_setprio 1
	v_mfma_f32_16x16x32_bf16 v[92:95], v[170:173], v[192:195], v[92:95]
	v_mfma_f32_16x16x32_bf16 v[88:91], v[178:181], v[192:195], v[88:91]
	v_mfma_f32_16x16x32_bf16 v[84:87], v[170:173], v[200:203], v[84:87]
	v_mfma_f32_16x16x32_bf16 v[80:83], v[178:181], v[200:203], v[80:83]
	v_mfma_f32_16x16x32_bf16 v[76:79], v[170:173], v[228:231], v[76:79]
	v_mfma_f32_16x16x32_bf16 v[72:75], v[178:181], v[228:231], v[72:75]
	v_mfma_f32_16x16x32_bf16 v[68:71], v[170:173], v[236:239], v[68:71]
	v_mfma_f32_16x16x32_bf16 v[64:67], v[178:181], v[236:239], v[64:67]
	v_mfma_f32_16x16x32_bf16 v[92:95], v[174:177], v[196:199], v[92:95]
	v_mfma_f32_16x16x32_bf16 v[88:91], v[188:191], v[196:199], v[88:91]
	v_mfma_f32_16x16x32_bf16 v[84:87], v[174:177], v[224:227], v[84:87]
	v_mfma_f32_16x16x32_bf16 v[80:83], v[188:191], v[224:227], v[80:83]
	v_mfma_f32_16x16x32_bf16 v[76:79], v[174:177], v[232:235], v[76:79]
	v_mfma_f32_16x16x32_bf16 v[72:75], v[188:191], v[232:235], v[72:75]
	v_mfma_f32_16x16x32_bf16 v[68:71], v[174:177], v[240:243], v[68:71]
	v_mfma_f32_16x16x32_bf16 v[64:67], v[188:191], v[240:243], v[64:67]
	s_setprio 2
	s_barrier
; #define PG8_STAGE(bufoff, gbase, voff) do { _Pragma("unroll") for (int _i = 0; _i < 2; ++_i) \
;         __builtin_amdgcn_global_load_lds((const unsigned*)((const char*)(gbase) + (voff)[_i]), (LAS unsigned*)(lds + (bufoff) + ldsw + _i * 8192), 16, 0, 0); } while (0)
; #define PG8_LDA(dst, b, h) do { _Pragma("unroll") for (int m = 0; m < 4; ++m) _Pragma("unroll") for (int k = 0; k < 2; ++k) dst[m][k] = *(const LAS bf16x8*)(lds + PG8_SA(b, h) + aoff + m * 2048 + k * 1024); } while (0)
; #define PG8_MMA(ai, bj, At, Bt) do { __builtin_amdgcn_s_setprio(1); _Pragma("unroll") for (int m = 0; m < 4; ++m) _Pragma("unroll") for (int n = 0; n < 2; ++n) _Pragma("unroll") for (int k = 0; k < 2; ++k) \
;         acc[ai][bj][m][n] = __builtin_amdgcn_mfma_f32_16x16x32_bf16(Bt[n][k], At[m][k], acc[ai][bj][m][n], 0, 0, 0); __builtin_amdgcn_s_setprio(0); } while (0)
; #define PG8_WAIT_V(n) asm volatile("s_waitcnt vmcnt(" #n ")" ::: "memory")
; #define PG8_WAIT_L(n) asm volatile("s_waitcnt lgkmcnt(" #n ")" ::: "memory")
; #define PG8_BAR __builtin_amdgcn_s_barrier()
; #define PG8_SCHED __builtin_amdgcn_sched_barrier(0)
;     ...
;             PG8_LDA(At, 1, 1); PG8_STAGE(PG8_SB(1, 0), b3, voffB); PG8_STAGE(PG8_SB(1, 1), b3 + hstepB, voffB); PG8_STAGE(PG8_SA(1, 0), a3, voffA);
;             PG8_WAIT_V(8); PG8_WAIT_L(0); PG8_BAR; PG8_MMA(1, 0, At, B0); PG8_MMA(1, 1, At, B1); PG8_BAR; PG8_SCHED;
;         }
;         if (wr == 0) PG8_BAR;
	s_add_i32 s2, s9, s40
	v_lshl_add_u64 v[212:213], v[244:245], 0, s[70:71]
	s_mov_b32 m0, s2
	ds_read_b128 v[192:195], v149 offset:49152
	ds_read_b128 v[196:199], v149 offset:50176
	ds_read_b128 v[200:203], v149 offset:51200
	ds_read_b128 v[224:227], v149 offset:52224
	ds_read_b128 v[228:231], v149 offset:53248
	ds_read_b128 v[232:235], v149 offset:54272
	ds_read_b128 v[236:239], v149 offset:55296
	ds_read_b128 v[240:243], v149 offset:56320
	global_load_lds_dwordx4 v[212:213], off
	v_lshl_add_u64 v[212:213], v[246:247], 0, s[70:71]
	s_add_i32 m0, s2, 0x2000
	s_add_i32 s2, s26, s40
	global_load_lds_dwordx4 v[212:213], off
	v_lshl_add_u64 v[212:213], v[248:249], 0, s[70:71]
	s_mov_b32 m0, s2
	v_lshl_add_u64 v[204:205], v[204:205], 0, s[70:71]
	global_load_lds_dwordx4 v[212:213], off
	s_add_i32 m0, s2, 0x2000
	s_nop 0
	global_load_lds_dwordx4 v[204:205], off
	v_lshl_add_u64 v[204:205], v[250:251], 0, s[70:71]
	s_mov_b32 m0, s51
	s_nop 0
	global_load_lds_dwordx4 v[204:205], off
	v_lshl_add_u64 v[204:205], v[218:219], 0, s[70:71]
	s_mov_b32 m0, s64
	s_nop 0
	global_load_lds_dwordx4 v[204:205], off
	s_waitcnt vmcnt(8)
	s_waitcnt lgkmcnt(0)
	s_barrier
	s_setprio 1
	s_waitcnt lgkmcnt(0)
	v_mfma_f32_16x16x32_bf16 v[60:63], v[154:157], v[192:195], v[60:63]
	v_mfma_f32_16x16x32_bf16 v[56:59], v[162:165], v[192:195], v[56:59]
	v_mfma_f32_16x16x32_bf16 v[52:55], v[154:157], v[200:203], v[52:55]
	v_mfma_f32_16x16x32_bf16 v[48:51], v[162:165], v[200:203], v[48:51]
	v_mfma_f32_16x16x32_bf16 v[44:47], v[154:157], v[228:231], v[44:47]
	v_mfma_f32_16x16x32_bf16 v[40:43], v[162:165], v[228:231], v[40:43]
	v_mfma_f32_16x16x32_bf16 v[36:39], v[154:157], v[236:239], v[36:39]
	v_mfma_f32_16x16x32_bf16 v[32:35], v[162:165], v[236:239], v[32:35]
	v_mfma_f32_16x16x32_bf16 v[60:63], v[158:161], v[196:199], v[60:63]
	v_mfma_f32_16x16x32_bf16 v[56:59], v[166:169], v[196:199], v[56:59]
	v_mfma_f32_16x16x32_bf16 v[52:55], v[158:161], v[224:227], v[52:55]
	v_mfma_f32_16x16x32_bf16 v[48:51], v[166:169], v[224:227], v[48:51]
	v_mfma_f32_16x16x32_bf16 v[44:47], v[158:161], v[232:235], v[44:47]
	v_mfma_f32_16x16x32_bf16 v[40:43], v[166:169], v[232:235], v[40:43]
	v_mfma_f32_16x16x32_bf16 v[36:39], v[158:161], v[240:243], v[36:39]
	v_mfma_f32_16x16x32_bf16 v[32:35], v[166:169], v[240:243], v[32:35]
	s_setprio 0
	s_setprio 1
	v_mfma_f32_16x16x32_bf16 v[28:31], v[170:173], v[192:195], v[28:31]
	v_mfma_f32_16x16x32_bf16 v[24:27], v[178:181], v[192:195], v[24:27]
	v_mfma_f32_16x16x32_bf16 v[20:23], v[170:173], v[200:203], v[20:23]
	v_mfma_f32_16x16x32_bf16 v[16:19], v[178:181], v[200:203], v[16:19]
	v_mfma_f32_16x16x32_bf16 v[12:15], v[170:173], v[228:231], v[12:15]
	v_mfma_f32_16x16x32_bf16 v[8:11], v[178:181], v[228:231], v[8:11]
	v_mfma_f32_16x16x32_bf16 v[4:7], v[170:173], v[236:239], v[4:7]
	v_mfma_f32_16x16x32_bf16 v[0:3], v[178:181], v[236:239], v[0:3]
	v_mfma_f32_16x16x32_bf16 v[28:31], v[174:177], v[196:199], v[28:31]
	v_mfma_f32_16x16x32_bf16 v[24:27], v[188:191], v[196:199], v[24:27]
	v_mfma_f32_16x16x32_bf16 v[20:23], v[174:177], v[224:227], v[20:23]
	v_mfma_f32_16x16x32_bf16 v[16:19], v[188:191], v[224:227], v[16:19]
	v_mfma_f32_16x16x32_bf16 v[12:15], v[174:177], v[232:235], v[12:15]
	v_mfma_f32_16x16x32_bf16 v[8:11], v[188:191], v[232:235], v[8:11]
	v_mfma_f32_16x16x32_bf16 v[4:7], v[174:177], v[240:243], v[4:7]
	v_mfma_f32_16x16x32_bf16 v[0:3], v[188:191], v[240:243], v[0:3]
	s_setprio 2
	s_barrier
	s_add_u32 s0, s0, 0x100
	s_addc_u32 s1, s1, 0
	v_lshl_add_u64 v[146:147], v[146:147], 0, s[94:95]
	v_lshl_add_u64 v[144:145], v[144:145], 0, s[94:95]
	s_cmp_ge_u32 s8, s48
	s_mov_b32 s2, s8
	s_cbranch_scc0 .LBB0_416
	v_readlane_b32 s0, v254, 45
	v_readlane_b32 s1, v254, 46
	s_and_b64 vcc, exec, s[0:1]
	s_cbranch_vccz .LBB0_419
	s_barrier
